# attention loop first half: next-tile global loads interleaved into the QK MFMA block instead of ahead of the K-fragment reads
# baseline (speedup 1.0000x reference)
.Lq1_body:
	ds_read_b128 v[44:47], v214 offset:35840
	ds_read_b128 v[72:75], v214 offset:35904
	ds_read_b128 v[92:95], v214 offset:40192
	ds_read_b128 v[112:115], v214 offset:40256
	ds_read_b128 v[132:135], v214 offset:44544
	ds_read_b128 v[148:151], v214 offset:44608
	ds_read_b128 v[136:139], v214 offset:48896
	ds_read_b128 v[152:155], v214 offset:48960
	s_waitcnt lgkmcnt(7)
	v_mfma_f32_16x16x32_bf16 v[140:143], v[44:47], v[8:11], 0
	v_mfma_f32_16x16x32_bf16 v[44:47], v[44:47], v[20:23], 0
	global_load_dwordx4 v[28:31], v202, s[100:101] offset:-128
	s_waitcnt lgkmcnt(1)
	v_mfma_f32_16x16x32_bf16 v[156:159], v[92:95], v[8:11], 0
	v_mfma_f32_16x16x32_bf16 v[92:95], v[92:95], v[20:23], 0
	global_load_dwordx4 v[32:35], v202, s[100:101]
	v_mfma_f32_16x16x32_bf16 v[160:163], v[132:135], v[8:11], 0
	v_mfma_f32_16x16x32_bf16 v[132:135], v[132:135], v[20:23], 0
	global_load_dwordx4 v[4:7], v203, s[100:101] offset:-128
	v_mfma_f32_16x16x32_bf16 v[164:167], v[136:139], v[8:11], 0
	v_mfma_f32_16x16x32_bf16 v[168:171], v[136:139], v[20:23], 0
	global_load_dwordx4 v[12:15], v203, s[100:101]
	v_mfma_f32_16x16x32_bf16 v[144:147], v[72:75], v[16:19], v[140:143]
	v_mfma_f32_16x16x32_bf16 v[136:139], v[72:75], v[24:27], v[44:47]
	v_mfma_f32_16x16x32_bf16 v[44:47], v[112:115], v[16:19], v[156:159]
	v_mfma_f32_16x16x32_bf16 v[92:95], v[112:115], v[24:27], v[92:95]
	v_mfma_f32_16x16x32_bf16 v[140:143], v[148:151], v[16:19], v[160:163]
	v_mfma_f32_16x16x32_bf16 v[132:135], v[148:151], v[24:27], v[132:135]
	s_waitcnt lgkmcnt(0)
	v_mfma_f32_16x16x32_bf16 v[72:75], v[152:155], v[16:19], v[164:167]
	v_mfma_f32_16x16x32_bf16 v[112:115], v[152:155], v[24:27], v[168:171]
	s_cmp_eq_u32 s98, 0
	s_cbranch_scc1 .LBB0_859
	v_sub_f32_e32 v147, v147, v196
	v_sub_f32_e32 v146, v146, v196
	v_sub_f32_e32 v145, v145, v196
	v_sub_f32_e32 v144, v144, v196
	v_sub_f32_e32 v47, v47, v196
	v_sub_f32_e32 v46, v46, v196
	v_sub_f32_e32 v45, v45, v196
	v_sub_f32_e32 v44, v44, v196
	v_sub_f32_e32 v143, v143, v196
	v_sub_f32_e32 v142, v142, v196
	v_sub_f32_e32 v141, v141, v196
	v_sub_f32_e32 v140, v140, v196
	v_sub_f32_e32 v75, v75, v196
	v_sub_f32_e32 v74, v74, v196
	v_sub_f32_e32 v73, v73, v196
	v_sub_f32_e32 v72, v72, v196
	v_sub_f32_e32 v139, v139, v197
	v_sub_f32_e32 v138, v138, v197
	v_sub_f32_e32 v137, v137, v197
	v_sub_f32_e32 v136, v136, v197
	v_sub_f32_e32 v95, v95, v197
	v_sub_f32_e32 v94, v94, v197
	v_sub_f32_e32 v93, v93, v197
	v_sub_f32_e32 v92, v92, v197
	v_sub_f32_e32 v135, v135, v197
	v_sub_f32_e32 v134, v134, v197
	v_sub_f32_e32 v133, v133, v197
	v_sub_f32_e32 v132, v132, v197
	v_sub_f32_e32 v115, v115, v197
	v_sub_f32_e32 v114, v114, v197
	v_sub_f32_e32 v113, v113, v197
	v_sub_f32_e32 v112, v112, v197
